# weight transposition for layers 1-3 moved out of the prologue phase: done by the 128 workgroups that have only 3 in-proj GEMM tiles while the others run their 4th (same code, per-layer item range)
# speedup vs baseline: 1.0162x; 1.0162x over previous
; #define LAS __attribute__((address_space(3)))
; __device__ __forceinline__ unsigned xb_add(unsigned* p, unsigned v) { return __hip_atomic_fetch_add(p, v, __ATOMIC_RELAXED, __HIP_MEMORY_SCOPE_AGENT); }
; __device__ __forceinline__ unsigned xb_xcc_id() { return (unsigned)__builtin_amdgcn_s_getreg((3 << 11) | 20) & 0xFu; }
; __global__ void __launch_bounds__(512) fwd_kernel(Params p_arg) {
;     extern __shared__ __attribute__((aligned(16))) unsigned char smem[];
;     LAS unsigned char* lds = (LAS unsigned char*)smem;
;     cg::grid_group grid = cg::this_grid();
;     const int ph_lo = p_arg.ph_lo, ph_hi = p_arg.ph_hi;
;     unsigned nbar = 0;
;     unsigned* const xbar = (unsigned*)(p_arg.ws + OFF_BAR); const unsigned xcc = xb_xcc_id(); unsigned xb_nloc = 0u, xb_nx = 0u;
;     if (threadIdx.x == 0) (void)xb_add(&xbar[XB_XCNT(xcc)], 1u);
;     if (ph_lo < 0) grid.sync();
;     for (int ph = ph_lo; ph < ph_hi; ++ph)
;     for (int rep = 0; rep < 1 + ((DUP_MASK >> (ph == 0 ? 0 : (ph == 1 + 7 * DEPTH ? 31 : 1 + (ph - 1) % 7))) & 1); ++rep) {
;         if (ph >= 1 && ph < 1 + 7 * DEPTH && (ph - 1) % 7 == 3) continue;
;         if (ph > ph_lo || rep > 0) {
;             ++nbar;
;             grid_barrier(xbar, xcc, xb_nloc, xb_nx);
;         }
;         KP p = (KP)__builtin_amdgcn_kernarg_segment_ptr();
;         asm volatile("" : "+s"(p));
;         unsigned char* ws = p->ws;
;         int tid = threadIdx.x; asm volatile("" : "+v"(tid));
;         const int lane = tid & 63, wave = tid >> 6;
;         const int gw = blockIdx.x * 8 + wave, NGW = gridDim.x * 8;
.LBB0_16:
	s_add_u32 s4, s84, 0x1a0b0200
	s_addc_u32 s5, s85, 0
	s_add_u32 s42, s84, 0x1a0b0400
	s_addc_u32 s43, s85, 0
	s_add_u32 s44, s84, 0x1a0b0500
	s_addc_u32 s45, s85, 0
	s_add_u32 s46, s84, 0x1a0b0600
	s_addc_u32 s47, s85, 0
	s_add_u32 s48, s84, 0x1a0b0700
	s_addc_u32 s49, s85, 0
	s_add_u32 s54, s84, 0x1a0b0800
	s_addc_u32 s55, s85, 0
	s_add_u32 s60, s84, 0x1a0b0900
	s_addc_u32 s61, s85, 0
	s_add_u32 s88, s84, 0x1a0b0a00
	s_addc_u32 s89, s85, 0
	s_add_u32 s90, s84, 0x1a0b0b00
	s_addc_u32 s91, s85, 0
	s_add_u32 s92, s84, 0x1a0b0c00
	s_addc_u32 s93, s85, 0
	s_add_u32 s94, s84, 0x1a0b0d00
	s_addc_u32 s95, s85, 0
	s_add_u32 s22, s84, 0x1a0b0e00
	v_writelane_b32 v253, s4, 2
	s_addc_u32 s23, s85, 0
	v_mov_b32_e32 v1, 0
	v_writelane_b32 v253, s5, 3
	s_add_u32 s4, s84, 0x1a0b0f00
	s_addc_u32 s5, s85, 0
	v_writelane_b32 v253, s4, 4
	s_mov_b32 s4, 0
	s_nop 0
	v_writelane_b32 v252, s4, 62
	v_writelane_b32 v252, s92, 0
	s_mov_b32 s14, 0x6dc9c883
	v_writelane_b32 v253, s5, 5
	s_add_u32 s4, s84, 0x1a0b1000
	s_addc_u32 s5, s85, 0
	v_writelane_b32 v253, s4, 6
	s_mov_b32 s16, 0x54442d18
	v_mbcnt_lo_u32_b32 v0, -1, 0
	v_writelane_b32 v253, s5, 7
	s_add_u32 s4, s84, 0x1a0b1100
	s_addc_u32 s5, s85, 0
	v_writelane_b32 v253, s4, 8
	v_writelane_b32 v252, s93, 1
	v_mov_b32_e32 v188, 1
	v_writelane_b32 v253, s5, 9
	s_add_u32 s4, s84, 0x1a0b1200
	s_addc_u32 s5, s85, 0
	v_writelane_b32 v253, s4, 10
	v_mov_b32_e32 v189, 0x358637bd
	v_mov_b32_e32 v190, 0x260
	v_writelane_b32 v253, s5, 11
	s_add_u32 s4, s84, 0x1a0b1300
	s_addc_u32 s5, s85, 0
	v_writelane_b32 v253, s4, 12
	s_cmp_eq_u32 s3, 15
	s_mov_b32 s15, 0x3fc45f30
	v_writelane_b32 v253, s5, 13
	s_cselect_b64 s[4:5], -1, 0
	v_writelane_b32 v253, s4, 14
	s_cmp_eq_u32 s3, 14
	s_mov_b32 s17, 0xc01921fb
	v_writelane_b32 v253, s5, 15
	s_cselect_b64 s[4:5], -1, 0
	v_writelane_b32 v253, s4, 16
	s_cmp_eq_u32 s3, 13
	v_mov_b32_e32 v191, 0x3c0881c4
	v_writelane_b32 v253, s5, 17
	s_cselect_b64 s[4:5], -1, 0
	v_writelane_b32 v253, s4, 18
	s_cmp_eq_u32 s3, 12
	v_mov_b32_e32 v192, 0xbab64f3b
	v_writelane_b32 v253, s5, 19
	s_cselect_b64 s[4:5], -1, 0
	v_writelane_b32 v253, s4, 20
	s_cmp_eq_u32 s3, 11
	v_mbcnt_hi_u32_b32 v193, -1, v0
	v_writelane_b32 v253, s5, 21
	s_cselect_b64 s[4:5], -1, 0
	v_writelane_b32 v253, s4, 22
	s_cmp_eq_u32 s3, 10
	v_mov_b64_e32 v[164:165], 0x200
	v_writelane_b32 v253, s5, 23
	s_cselect_b64 s[4:5], -1, 0
	v_writelane_b32 v253, s4, 24
	s_cmp_eq_u32 s3, 9
	v_mov_b32_e32 v194, 0xf149f2ca
	v_writelane_b32 v253, s5, 25
	s_cselect_b64 s[4:5], -1, 0
	v_writelane_b32 v253, s4, 26
	s_cmp_eq_u32 s3, 8
	v_mov_b32_e32 v195, 0xc0
	v_writelane_b32 v253, s5, 27
	s_cselect_b64 s[4:5], -1, 0
	v_writelane_b32 v253, s4, 28
	s_cmp_eq_u32 s3, 7
	v_mov_b32_e32 v196, 0x70
	v_writelane_b32 v253, s5, 29
	s_cselect_b64 s[4:5], -1, 0
	v_writelane_b32 v253, s4, 30
	s_cmp_eq_u32 s3, 6
	v_mov_b32_e32 v197, 0x71
	v_writelane_b32 v253, s5, 31
	s_cselect_b64 s[4:5], -1, 0
	v_writelane_b32 v253, s4, 32
	s_cmp_eq_u32 s3, 5
	v_mov_b32_e32 v198, 5
	v_writelane_b32 v253, s5, 33
	s_cselect_b64 s[4:5], -1, 0
	v_writelane_b32 v253, s4, 34
	s_cmp_eq_u32 s3, 4
	v_mov_b32_e32 v199, 2
	v_writelane_b32 v253, s5, 35
	s_cselect_b64 s[4:5], -1, 0
	v_writelane_b32 v253, s4, 36
	s_cmp_eq_u32 s3, 3
	v_mov_b32_e32 v200, 3
	v_writelane_b32 v253, s5, 37
	s_cselect_b64 s[4:5], -1, 0
	v_writelane_b32 v253, s4, 38
	s_cmp_eq_u32 s3, 2
	v_mov_b32_e32 v222, v1
	v_writelane_b32 v253, s5, 39
	s_cselect_b64 s[4:5], -1, 0
	v_writelane_b32 v253, s4, 40
	s_cmp_eq_u32 s3, 1
	v_mov_b32_e32 v223, v1
	v_writelane_b32 v253, s5, 41
	s_cselect_b64 s[4:5], -1, 0
	v_writelane_b32 v253, s4, 42
	s_cmp_eq_u32 s3, 0
	v_mov_b32_e32 v224, v1
	v_writelane_b32 v253, s5, 43
	s_cselect_b64 s[4:5], -1, 0
	s_lshl_b32 s3, s3, 8
	s_add_u32 s0, s0, s3
	v_writelane_b32 v253, s4, 44
	s_addc_u32 s1, s1, 0
	v_mov_b32_e32 v225, v1
	v_writelane_b32 v253, s5, 45
	s_add_u32 s4, s0, 0x1400
	s_addc_u32 s5, s1, 0
	v_writelane_b32 v253, s4, 46
	s_add_u32 s0, s0, 0x2400
	s_addc_u32 s1, s1, 0
	v_writelane_b32 v253, s5, 47
	v_writelane_b32 v253, s0, 48
	v_not_b32_e32 v201, 63
	v_not_b32_e32 v202, 31
	v_writelane_b32 v253, s1, 49
	s_add_u32 s0, s84, 0x1a0b3400
	s_addc_u32 s1, s85, 0
	v_writelane_b32 v253, s0, 50
	v_mov_b32_e32 v203, 0x7fc00000
	s_movk_i32 s39, 0x2000
	v_writelane_b32 v253, s1, 51
	s_add_u32 s0, s84, 0x1a0b3500
	s_addc_u32 s1, s85, 0
	v_writelane_b32 v253, s0, 52
	s_lshl_b32 s33, s52, 3
	s_lshl_b32 s20, s52, 9
	v_writelane_b32 v253, s1, 53
	s_lshl_b32 s0, s2, 3
	v_writelane_b32 v253, s0, 54
	s_lshl_b32 s0, s2, 9
	s_cmpk_lt_i32 s2, 0x200
	v_writelane_b32 v253, s0, 55
	s_cselect_b64 s[0:1], -1, 0
	v_writelane_b32 v253, s0, 56
	s_ashr_i32 s3, s2, 31
	s_ashr_i32 s53, s52, 31
	v_writelane_b32 v253, s1, 57
	s_lshr_b32 s0, s3, 29
	s_add_i32 s0, s2, s0
	s_ashr_i32 s1, s0, 3
	s_and_b32 s0, s0, -8
	s_sub_i32 s0, s2, s0
	s_lshl_b32 s4, s0, 6
	s_cmpk_lt_i32 s2, 0x800
	s_cselect_b64 s[6:7], -1, 0
	v_writelane_b32 v253, s6, 58
	s_lshl_b32 s5, s0, 8
	s_movk_i32 s56, 0x1fff
	v_writelane_b32 v253, s7, 59
	s_sub_u32 s6, 0x200, s2
	s_subb_u32 s7, 0, s3
	v_writelane_b32 v253, s6, 60
	s_cmpk_lt_i32 s2, 0x100
	s_movk_i32 s57, 0xc0
	v_writelane_b32 v253, s7, 61
	s_cselect_b64 s[6:7], -1, 0
	v_writelane_b32 v253, s6, 62
; #define LAS __attribute__((address_space(3)))
; __device__ __forceinline__ unsigned xb_add(unsigned* p, unsigned v) { return __hip_atomic_fetch_add(p, v, __ATOMIC_RELAXED, __HIP_MEMORY_SCOPE_AGENT); }
; __device__ __forceinline__ unsigned xb_xcc_id() { return (unsigned)__builtin_amdgcn_s_getreg((3 << 11) | 20) & 0xFu; }
;     __host__ __device__ bool next(int i, Unit& u) const {
;         const long L = (long)i * G + c; if (L >= nwg) return false;
;         int wgid = (int)L; { const int q = nwg / NXCD, r = nwg % NXCD, xcd = wgid % NXCD, off = wgid / NXCD; wgid = (xcd < r ? xcd * (q + 1) : r * (q + 1) + (xcd - r) * q) + off; }
;         const int nig = WGM * nN, gid = wgid / nig, fm = gid * WGM, gsz = (nM - fm) < WGM ? (nM - fm) : WGM;
;         u.pm = fm + ((wgid % nig) % gsz); u.pn = (wgid % nig) / gsz; return true;
; __global__ void __launch_bounds__(512) fwd_kernel(Params p_arg) {
;     extern __shared__ __attribute__((aligned(16))) unsigned char smem[];
;     LAS unsigned char* lds = (LAS unsigned char*)smem;
;     cg::grid_group grid = cg::this_grid();
;     const int ph_lo = p_arg.ph_lo, ph_hi = p_arg.ph_hi;
;     unsigned nbar = 0;
;     unsigned* const xbar = (unsigned*)(p_arg.ws + OFF_BAR); const unsigned xcc = xb_xcc_id(); unsigned xb_nloc = 0u, xb_nx = 0u;
;     if (threadIdx.x == 0) (void)xb_add(&xbar[XB_XCNT(xcc)], 1u);
;     if (ph_lo < 0) grid.sync();
;     for (int ph = ph_lo; ph < ph_hi; ++ph)
;     for (int rep = 0; rep < 1 + ((DUP_MASK >> (ph == 0 ? 0 : (ph == 1 + 7 * DEPTH ? 31 : 1 + (ph - 1) % 7))) & 1); ++rep) {
;         if (ph >= 1 && ph < 1 + 7 * DEPTH && (ph - 1) % 7 == 3) continue;
;         if (ph > ph_lo || rep > 0) {
;             ++nbar;
;             grid_barrier(xbar, xcc, xb_nloc, xb_nx);
;         }
;         KP p = (KP)__builtin_amdgcn_kernarg_segment_ptr();
;         asm volatile("" : "+s"(p));
;         unsigned char* ws = p->ws;
;         int tid = threadIdx.x; asm volatile("" : "+v"(tid));
;         const int lane = tid & 63, wave = tid >> 6;
;         const int gw = blockIdx.x * 8 + wave, NGW = gridDim.x * 8;
	s_cmpk_lt_i32 s2, 0x380
	s_mov_b32 s72, 0x10000
	v_writelane_b32 v253, s7, 63
	s_cselect_b64 s[6:7], -1, 0
	v_writelane_b32 v254, s6, 0
	s_cmp_lt_i32 s0, 0
	v_readlane_b32 s84, v253, 0
	v_writelane_b32 v254, s7, 1
	s_mul_i32 s6, s0, 0x41
	s_cselect_b32 s4, s6, s4
	s_mul_i32 s6, s0, 0x101
	s_cselect_b32 s5, s6, s5
	s_movk_i32 s6, 0x71
	s_cselect_b32 s6, s6, 0x70
	s_add_i32 s4, s4, s1
	s_ashr_i32 s7, s4, 31
	s_lshr_b32 s7, s7, 27
	s_add_i32 s7, s4, s7
	s_and_b32 s8, s7, 0xffe0
	s_sub_i32 s4, s4, s8
	s_bfe_i32 s8, s4, 0x80000
	s_bfe_u32 s8, s8, 0x3000c
	s_add_i32 s8, s4, s8
	s_and_b32 s9, s8, 0xf8
	s_add_i32 s5, s5, s1
	s_mul_i32 s0, s0, s6
	s_sub_i32 s4, s4, s9
	s_ashr_i32 s9, s5, 31
	s_add_i32 s0, s0, s1
	s_lshr_b32 s9, s9, 25
	s_mul_hi_i32 s1, s0, 0x92492493
	s_add_i32 s9, s5, s9
	s_add_i32 s1, s1, s0
	s_and_b32 s10, s9, 0xff80
	s_lshr_b32 s6, s1, 31
	s_ashr_i32 s1, s1, 5
	s_sub_i32 s5, s5, s10
	s_add_i32 s6, s1, s6
	s_bfe_i32 s10, s5, 0x80000
	s_mul_i32 s1, s6, 56
	s_bfe_u32 s10, s10, 0x3000c
	s_sub_i32 s0, s0, s1
	s_add_i32 s10, s5, s10
	s_bfe_i32 s1, s0, 0x80000
	s_and_b32 s11, s10, 0xf8
	s_bfe_u32 s1, s1, 0x3000c
	s_sub_i32 s5, s5, s11
	s_add_i32 s11, s0, s1
	s_and_b32 s1, s11, 0xf8
	s_sub_i32 s12, s0, s1
	s_ashr_i32 s0, s7, 5
	s_bfe_i32 s1, s8, 0x80000
	s_lshl_b32 s0, s0, 3
	s_sext_i32_i16 s7, s1
	s_sext_i32_i8 s1, s4
	s_add_i32 s8, s0, s1
	s_ashr_i32 s0, s9, 7
	s_bfe_i32 s1, s10, 0x80000
	s_lshl_b32 s0, s0, 3
	s_sext_i32_i16 s1, s1
	s_sext_i32_i8 s4, s5
	s_add_i32 s24, s0, s4
	s_ashr_i32 s0, s1, 3
	v_writelane_b32 v254, s0, 2
	s_lshr_b32 s0, s1, 3
	s_bfe_i64 s[0:1], s[0:1], 0x100000
	s_lshl_b64 s[0:1], s[0:1], 19
	v_writelane_b32 v254, s0, 3
	s_sext_i32_i8 s4, s12
	s_ashr_i32 s25, s24, 31
	v_writelane_b32 v254, s1, 4
	s_bfe_i32 s1, s11, 0x80000
	s_lshl_b32 s0, s6, 3
	s_sext_i32_i16 s1, s1
	s_add_i32 s4, s0, s4
	s_ashr_i32 s0, s1, 3
	v_writelane_b32 v254, s0, 5
	s_lshr_b32 s0, s1, 3
	s_bfe_i64 s[0:1], s[0:1], 0x100000
	s_lshl_b64 s[0:1], s[0:1], 19
	v_writelane_b32 v254, s0, 6
	s_ashr_i32 s5, s4, 31
	s_ashr_i32 s9, s8, 31
	v_writelane_b32 v254, s1, 7
	s_ashr_i32 s0, s7, 3
	v_writelane_b32 v254, s0, 8
	s_lshr_b32 s0, s7, 3
	s_bfe_i64 s[0:1], s[0:1], 0x100000
	s_lshl_b64 s[6:7], s[0:1], 21
	v_writelane_b32 v254, s6, 9
	s_lshl_b64 s[0:1], s[0:1], 19
	s_lshl_b32 s21, s52, 5
	v_writelane_b32 v254, s7, 10
	v_writelane_b32 v254, s0, 11
	s_mov_b64 s[6:7], s[86:87]
	s_lshl_b32 s50, s52, 8
	v_writelane_b32 v254, s1, 12
	s_lshl_b32 s0, s2, 5
	v_writelane_b32 v254, s0, 13
	s_lshl_b32 s0, s2, 8
	v_writelane_b32 v254, s0, 14
	s_lshl_b32 s0, s2, 6
	v_writelane_b32 v254, s0, 15
	s_addk_i32 s0, 0x680
	v_writelane_b32 v254, s0, 16
	s_lshl_b32 s0, s2, 10
	v_writelane_b32 v254, s0, 17
	s_lshl_b32 s0, s52, 1
	v_writelane_b32 v254, s0, 18
	s_add_i32 s0, 0, 0x20000
	v_writelane_b32 v254, s0, 19
	s_add_i32 s0, 0, 0x26000
	v_writelane_b32 v254, s0, 20
	s_add_i32 s0, 0, 0x27000
	v_writelane_b32 v254, s0, 21
	s_mov_b32 s0, 0
	v_writelane_b32 v254, s0, 22
	v_writelane_b32 v254, s0, 23
	s_mov_b32 s0, s24
	v_writelane_b32 v254, s0, 24
	s_lshl_b32 s51, s52, 6
	s_lshl_b32 s38, s52, 10
	v_writelane_b32 v254, s1, 25
	s_lshl_b64 s[0:1], s[24:25], 19
	v_writelane_b32 v254, s0, 26
	s_movk_i32 s59, 0x6000
	s_mov_b32 s62, 0xf800000
	v_writelane_b32 v254, s1, 27
	s_mov_b32 s0, s4
	v_writelane_b32 v254, s0, 28
	s_mov_b32 s63, 0x2aaaaaab
	s_movk_i32 s64, 0x110
	v_writelane_b32 v254, s1, 29
	s_lshl_b64 s[0:1], s[4:5], 19
	v_writelane_b32 v254, s0, 30
	s_movk_i32 s65, 0xe00
	s_movk_i32 s66, 0x9e
	v_writelane_b32 v254, s1, 31
	s_lshl_b64 s[0:1], s[8:9], 21
	v_writelane_b32 v254, s0, 32
	s_movk_i32 s67, 0x210
	s_movk_i32 s68, 0x3000
	v_writelane_b32 v254, s1, 33
	s_mov_b32 s0, s8
	v_writelane_b32 v254, s0, 34
	s_add_i32 s69, 0, 0x15800
	s_mov_b32 s73, 0xfe5163ab
	v_writelane_b32 v254, s1, 35
	s_lshl_b64 s[0:1], s[8:9], 19
	v_writelane_b32 v254, s0, 36
	s_mov_b32 s74, 0x3c439041
	s_mov_b32 s75, 0xdb629599
	v_writelane_b32 v254, s1, 37
	s_lshl_b64 s[0:1], s[52:53], 1
	v_writelane_b32 v254, s0, 38
	s_mov_b32 s76, 0xf534ddc0
	s_mov_b32 s77, 0xfc2757d1
	v_writelane_b32 v254, s1, 39
	v_writelane_b32 v254, s70, 40
	s_mov_b32 s78, 0x4e441529
	s_mov_b32 s79, 0xa2f9836e
	v_writelane_b32 v254, s71, 41
	v_writelane_b32 v254, s4, 42
	s_mov_b32 s80, 0x3fc90fda
	s_mov_b32 s81, 0xbfc90fda
	v_writelane_b32 v254, s5, 43
	v_writelane_b32 v254, s6, 44
	v_writelane_b32 v254, s7, 45
	v_writelane_b32 v254, s22, 46
	s_mov_b32 s82, s86
	s_mov_b32 s19, 0
	v_writelane_b32 v254, s23, 47
	v_writelane_b32 v254, s42, 48
	s_mov_b64 s[26:27], 0x80
	s_mov_b64 s[28:29], 0x100
	v_writelane_b32 v254, s43, 49
	v_writelane_b32 v254, s44, 50
	s_mov_b64 s[30:31], 0x800
	s_mov_b64 s[34:35], 0x6000
	v_writelane_b32 v254, s45, 51
	v_writelane_b32 v254, s46, 52
	v_readlane_b32 s85, v253, 1
	v_writelane_b32 v252, s94, 2
	v_writelane_b32 v254, s47, 53
	v_writelane_b32 v254, s48, 54
	v_writelane_b32 v252, s95, 3
	s_nop 0
	v_writelane_b32 v254, s49, 55
	v_writelane_b32 v254, s54, 56
	s_nop 1
	v_writelane_b32 v254, s55, 57
	v_writelane_b32 v254, s60, 58
	s_nop 1
	v_writelane_b32 v254, s61, 59
	v_writelane_b32 v254, s88, 60
	s_nop 1
	v_writelane_b32 v254, s89, 61
	v_writelane_b32 v254, s90, 62
	s_nop 1
	v_writelane_b32 v254, s91, 63
	s_branch .LBB0_20

; #define LAS __attribute__((address_space(3)))
; __device__ __forceinline__ void phase_prologue(KP p, LAS unsigned char* lds) {
;     ...
;     for (int it = gw; it < DEPTH * I_LAYER; it += NGW) {
;         const int l = it / I_LAYER; int r = it % I_LAYER;
;         if (r < I_IN) { transpose_item(p->w_in + (size_t)l * DM * DIN, DIN, p->mix_norm_g + l * DM, nullptr, (bf16_t*)(ws + OFF_WIN + l * SZ_WIN), DM, scr, r, lane); continue; } r -= I_IN;
; __global__ void __launch_bounds__(512) fwd_kernel(Params p_arg) {
;     ...
;         if (sub == 0) {
;             pg8::Gemm g{(const bf16_t*)(ws + OFF_HB), (const bf16_t*)(ws + OFF_WIN + l * SZ_WIN), M_TOK, DIN_P, DM};
;             S.init(M_TOK, DIN_P, gridDim.x, blockIdx.x);
;             LAS float* rstab = (LAS float*)(lds + pg8::STAGE_BYTES);
;             pg8::build_rs_table(rstab, S, (const float*)(ws + OFF_SSQA));
;             pg8::EpiScaleBf16<0> E{(bf16_t*)(ws + OFF_ZB), DIN_P, rstab};
;             pg8::gemm_phase(lds, g, S, E);
.LBB0_468:
	v_readlane_b32 s22, v254, 46
	v_readlane_b32 s23, v254, 47
	s_cmp_lt_u32 s2, 0x80
	s_cbranch_scc1 .LA_nooff
	s_movk_i32 s6, 0x159c
	s_cmp_eq_u32 s82, 1
	s_cbranch_scc1 .LA_off
	s_movk_i32 s6, 0x2b38
	s_cmp_eq_u32 s82, 8
	s_cbranch_scc1 .LA_off
	s_movk_i32 s6, 0x40d4
	s_cmp_eq_u32 s82, 15
	s_cbranch_scc0 .LA_nooff
.LA_off:
	s_nop 0
	v_writelane_b32 v252, s6, 62
	s_mov_b64 s[0:1], s[70:71]
	s_branch .LBB0_469

; __device__ __forceinline__ void phase_prologue(KP p, LAS unsigned char* lds) {
;     ...
;     for (int it = gw; it < DEPTH * I_LAYER; it += NGW) {
;         const int l = it / I_LAYER; int r = it % I_LAYER;
;         if (r < I_IN) { transpose_item(p->w_in + (size_t)l * DM * DIN, DIN, p->mix_norm_g + l * DM, nullptr, (bf16_t*)(ws + OFF_WIN + l * SZ_WIN), DM, scr, r, lane); continue; } r -= I_IN;
;         if (r < I_OUT) { transpose_item(p->w_out + (size_t)l * DM * DM, DM, p->group_norm_g + l * DM, nullptr, (bf16_t*)(ws + OFF_WOUT + l * SZ_WOUT), DM, scr, r, lane); continue; } r -= I_OUT;
;         if (r < I_FF1) { transpose_item(p->w_ff1 + (size_t)l * DM * DFF, DFF, p->ffn_norm_g + l * DM, nullptr, (bf16_t*)(ws + OFF_W1 + l * SZ_W1), DM, scr, r, lane); continue; } r -= I_FF1;
;         if (r < I_FF2) { transpose_item(p->w_ff2 + (size_t)l * DFF * DM, DM, nullptr, nullptr, (bf16_t*)(ws + OFF_W2 + l * SZ_W2), DFF, scr, r, lane); continue; } r -= I_FF2;
;         if (r < I_PW) { transpose_item(p->conv_pw_w + (size_t)l * 256 * 256, 256, nullptr, nullptr, (bf16_t*)(ws + OFF_PW + l * SZ_PW), 256, scr, r, lane); continue; } r -= I_PW;
;         if (r < I_UQ) { transpose_item(p->mla_w_uq + (size_t)l * 192 * 384, 384, p->mla_q_norm_g + l * 192, nullptr, (bf16_t*)(ws + OFF_UQ + l * SZ_UQ), 192, scr, r, lane); continue; } r -= I_UQ;
;         if (r < I_UKV) { transpose_item(p->mla_w_ukv + (size_t)l * 128 * 512, 512, p->mla_kv_norm_g + l * 128, nullptr, (bf16_t*)(ws + OFF_UKV + l * SZ_UKV), 128, scr, r, lane); continue; } r -= I_UKV;
;         { const int g = r >> 1, sub = r & 1;
;           transpose_item(p->pool_w + (size_t)(l * 4 + g) * 64 * 64, 64, nullptr, p->pool_scale + l * 256 + g * 64, (bf16_t*)(ws + OFF_POOL + l * SZ_POOL) + g * 64 * 64, 64, scr, sub, lane); }
.LBB0_469:
	s_waitcnt vmcnt(0)
	v_mov_b32_e32 v22, v167
	v_readlane_b32 s4, v253, 54
	v_readlane_b32 s6, v252, 62
	s_movk_i32 s101, 0x159c
	s_mov_b32 s100, s33
	s_nop 1
	s_cmp_eq_u32 s6, 0
	s_cbranch_scc1 .Lpro_go
	s_sub_i32 s4, s2, 0x80
	s_lshl_b32 s4, s4, 3
	s_add_i32 s4, s4, s6
	s_add_i32 s101, s6, 0x159c
	s_movk_i32 s100, 0x400
.Lpro_go:
	v_ashrrev_i32_e32 v11, 6, v22
	v_and_b32_e32 v13, 63, v22
	v_add_u32_e32 v64, s4, v11
	v_cmp_gt_i32_e32 vcc, s101, v64
	s_and_saveexec_b64 s[4:5], vcc
	s_cbranch_execz .LBB0_528
	s_waitcnt lgkmcnt(0)
	s_add_u32 s8, s94, 0x5790000
	s_addc_u32 s9, s95, 0
	s_add_u32 s10, s94, 0x5710000
	s_addc_u32 s11, s95, 0
	s_add_u32 s12, s94, 0x5680000
	s_addc_u32 s13, s95, 0
	s_add_u32 s22, s94, 0x5600000
	s_addc_u32 s23, s95, 0
	s_add_u32 s24, s94, 0x3600000
	s_movk_i32 s6, 0x2100
	s_addc_u32 s25, s95, 0
	v_mul_lo_u32 v0, v11, s6
	v_lshrrev_b32_e32 v23, 5, v13
	v_and_b32_e32 v10, 31, v22
	s_add_u32 s36, s94, 0x1600000
	v_add_u32_e32 v2, 0, v0
	v_and_b32_e32 v3, 7, v22
	v_lshrrev_b32_e32 v24, 3, v13
	v_lshlrev_b32_e32 v4, 2, v10
	v_mul_u32_u24_e32 v5, 0x84, v23
	s_addc_u32 s37, s95, 0
	v_readlane_b32 s6, v254, 14
	v_lshlrev_b32_e32 v0, 6, v23
	v_add3_u32 v25, v2, v4, v5
	v_lshlrev_b32_e32 v12, 3, v3
	v_mul_u32_u24_e32 v3, 0x420, v3
	v_lshlrev_b32_e32 v4, 2, v24
	s_add_u32 s44, s94, 0xe00000
	v_lshlrev_b32_e32 v30, 5, v64
	v_readlane_b32 s6, v254, 16
	v_add3_u32 v26, v2, v3, v4
	v_or_b32_e32 v27, 8, v24
	v_or_b32_e32 v28, 16, v24
	v_or_b32_e32 v29, 24, v24
	s_addc_u32 s45, s95, 0
	v_lshlrev_b32_e32 v31, 3, v64
	v_add_u32_e32 v31, 0x680, v31
	s_mov_b64 s[46:47], 0
	v_lshlrev_b32_e32 v14, 2, v0
	v_mov_b32_e32 v32, v64
	s_branch .LBB0_473

; __device__ __forceinline__ void phase_prologue(KP p, LAS unsigned char* lds) {
;     ...
;     for (int it = gw; it < DEPTH * I_LAYER; it += NGW) {
.LBB0_472:
	s_or_b64 exec, exec, s[6:7]
	v_add_u32_e32 v32, s100, v32
	s_add_i32 s6, s101, -1
	v_cmp_lt_i32_e32 vcc, s6, v32
	v_lshlrev_b32_e32 v30, 5, v32
	s_or_b64 s[46:47], vcc, s[46:47]
	v_lshlrev_b32_e32 v31, 3, v32
	v_add_u32_e32 v31, 0x680, v31
	s_andn2_b64 exec, exec, s[46:47]
	s_cbranch_execz .LBB0_528

; __device__ __forceinline__ void phase_prologue(KP p, LAS unsigned char* lds) {
;     ...
;     }
;     const int gt = blockIdx.x * 512 + tid, NGT = gridDim.x * 512;
;     for (int i = gt; i < DEPTH * 160 * (DM / 8); i += NGT) { const int l = i / (160 * 128), r = i % (160 * 128);
;         *(u32x4*)((bf16_t*)(ws + OFF_WIN + l * SZ_WIN) + (size_t)(DIN + r / 128) * DM + (r % 128) * 8) = (u32x4){0u, 0u, 0u, 0u}; }
.LBB0_528:
	s_or_b64 exec, exec, s[4:5]
	v_readlane_b32 s6, v252, 62
	s_nop 3
	s_cmp_eq_u32 s6, 0
	s_cbranch_scc1 .Lpro_cont
	s_mov_b32 s6, 0
	s_nop 0
	v_writelane_b32 v252, s6, 62
	v_readlane_b32 s22, v254, 46
	v_readlane_b32 s23, v254, 47
	s_mov_b64 s[4:5], -1
	s_branch .Ltramp_17
.Lpro_cont:
	v_readlane_b32 s4, v253, 55
	s_nop 1
	v_add_u32_e32 v6, s4, v22
	s_mov_b32 s4, 0x14000
	v_cmp_gt_i32_e32 vcc, s4, v6
	s_and_saveexec_b64 s[4:5], vcc
	s_cbranch_execz .LBB0_531
	s_mov_b64 s[6:7], 0
	s_waitcnt lgkmcnt(0)
	v_mov_b32_e32 v2, v6
